# GQA loop: the two s_mul_i32 per iteration ((s0&64)*0x90 LDS double-buffer offset) replaced by s_bitcmp + s_cselect
# speedup vs baseline: 1.0113x; 1.0019x over previous
.Lgq_top:
	s_bitcmp1_b32 s0, 6
	s_cselect_b32 s6, 0x2400, 0
	v_add_u32_e32 v159, s6, v156
	v_add_u32_e32 v172, s6, v157
	ds_read_b128 v[112:115], v159
	ds_read_b128 v[116:119], v159 offset:32
	ds_read_b128 v[120:123], v159 offset:64
	ds_read_b128 v[124:127], v159 offset:96
	ds_read_b128 v[128:131], v159 offset:4608
	ds_read_b128 v[132:135], v159 offset:4640
	ds_read_b128 v[136:139], v159 offset:4672
	ds_read_b128 v[140:143], v159 offset:4704
	s_cmpk_eq_i32 s0, 0x10c0
	s_cbranch_scc1 .Lgq_noload
	s_cmp_lt_u32 s5, 3
	s_cselect_b32 s1, 8, 12
	s_cselect_b32 s6, 0x8000, s8
	s_lshl_b32 s1, s12, s1
	s_add_i32 s1, s6, s1
	s_add_i32 s1, s1, s0
	v_add_u32_e32 v111, s1, v110
	v_mad_i64_i32 v[250:251], s[6:7], v111, s43, v[96:97]
	v_add_u32_e32 v111, s1, v109
	global_load_dwordx4 v[92:95], v[250:251], off
	global_load_dwordx4 v[84:87], v[100:101], off
	v_mad_i64_i32 v[250:251], s[6:7], v111, s43, v[96:97]
	s_nop 0
	global_load_dwordx4 v[88:91], v[250:251], off
	global_load_dwordx4 v[80:83], v[102:103], off
	v_lshl_add_u64 v[100:101], v[100:101], 0, s[10:11]
	v_lshl_add_u64 v[102:103], v[102:103], 0, s[10:11]
.Lgq_noload:
	v_exp_f32_e32 v32, v32
	v_exp_f32_e32 v33, v33
	v_exp_f32_e32 v34, v34
	v_exp_f32_e32 v35, v35
	s_waitcnt lgkmcnt(7)
	v_mfma_f32_32x32x16_bf16 v[48:63], v[112:115], v[76:79], 0
	v_exp_f32_e32 v36, v36
	v_exp_f32_e32 v37, v37
	v_add_f32_e32 v246, v32, v246
	v_add_f32_e32 v247, v33, v247
	v_cvt_pk_bf16_f32 v238, v32, v33
	s_waitcnt lgkmcnt(6)
	v_mfma_f32_32x32x16_bf16 v[48:63], v[116:119], v[72:75], v[48:63]
	v_exp_f32_e32 v38, v38
	v_exp_f32_e32 v39, v39
	v_add_f32_e32 v248, v34, v248
	v_add_f32_e32 v249, v35, v249
	v_cvt_pk_bf16_f32 v239, v34, v35
	s_waitcnt lgkmcnt(5)
	v_mfma_f32_32x32x16_bf16 v[48:63], v[120:123], v[68:71], v[48:63]
	v_exp_f32_e32 v40, v40
	v_exp_f32_e32 v41, v41
	v_add_f32_e32 v246, v36, v246
	v_add_f32_e32 v247, v37, v247
	v_cvt_pk_bf16_f32 v240, v36, v37
	s_waitcnt lgkmcnt(4)
	v_mfma_f32_32x32x16_bf16 v[48:63], v[124:127], v[64:67], v[48:63]
	v_exp_f32_e32 v42, v42
	v_exp_f32_e32 v43, v43
	v_add_f32_e32 v248, v38, v248
	v_add_f32_e32 v249, v39, v249
	v_cvt_pk_bf16_f32 v241, v38, v39
	v_mfma_f32_32x32x16_bf16 v[0:15], v[144:147], v[200:203], v[0:15]
	ds_read_b128 v[144:147], v172
	v_exp_f32_e32 v44, v44
	v_exp_f32_e32 v45, v45
	v_add_f32_e32 v246, v40, v246
	v_add_f32_e32 v247, v41, v247
	v_cvt_pk_bf16_f32 v242, v40, v41
	v_mfma_f32_32x32x16_bf16 v[16:31], v[164:167], v[200:203], v[16:31]
	ds_read_b128 v[164:167], v172 offset:4608
	v_exp_f32_e32 v46, v46
	v_exp_f32_e32 v47, v47
	v_add_f32_e32 v248, v42, v248
	v_add_f32_e32 v249, v43, v249
	v_cvt_pk_bf16_f32 v243, v42, v43
	v_mfma_f32_32x32x16_bf16 v[0:15], v[148:151], v[204:207], v[0:15]
	ds_read_b128 v[148:151], v172 offset:32
	v_add_f32_e32 v246, v44, v246
	v_add_f32_e32 v247, v45, v247
	v_cvt_pk_bf16_f32 v244, v44, v45
	v_add_f32_e32 v248, v46, v248
	v_add_f32_e32 v249, v47, v249
	v_mfma_f32_32x32x16_bf16 v[16:31], v[168:171], v[204:207], v[16:31]
	ds_read_b128 v[168:171], v172 offset:4640
	v_cvt_pk_bf16_f32 v245, v46, v47
	v_exp_f32_e32 v48, v48
	v_exp_f32_e32 v49, v49
	v_exp_f32_e32 v50, v50
	s_waitcnt lgkmcnt(7)
	v_mfma_f32_32x32x16_bf16 v[32:47], v[128:131], v[76:79], 0
	v_exp_f32_e32 v51, v51
	v_exp_f32_e32 v52, v52
	v_add_f32_e32 v246, v48, v246
	v_add_f32_e32 v247, v49, v247
	v_cvt_pk_bf16_f32 v200, v48, v49
	s_waitcnt lgkmcnt(6)
	v_mfma_f32_32x32x16_bf16 v[32:47], v[132:135], v[72:75], v[32:47]
	v_exp_f32_e32 v53, v53
	v_exp_f32_e32 v54, v54
	v_add_f32_e32 v248, v50, v248
	v_add_f32_e32 v249, v51, v249
	v_cvt_pk_bf16_f32 v201, v50, v51
	s_waitcnt lgkmcnt(5)
	v_mfma_f32_32x32x16_bf16 v[32:47], v[136:139], v[68:71], v[32:47]
	v_exp_f32_e32 v55, v55
	v_exp_f32_e32 v56, v56
	v_add_f32_e32 v246, v52, v246
	v_add_f32_e32 v247, v53, v247
	v_cvt_pk_bf16_f32 v202, v52, v53
	s_waitcnt lgkmcnt(4)
	v_mfma_f32_32x32x16_bf16 v[32:47], v[140:143], v[64:67], v[32:47]
	v_exp_f32_e32 v57, v57
	v_exp_f32_e32 v58, v58
	v_add_f32_e32 v248, v54, v248
	v_add_f32_e32 v249, v55, v249
	v_cvt_pk_bf16_f32 v203, v54, v55
	v_mfma_f32_32x32x16_bf16 v[0:15], v[152:155], v[238:241], v[0:15]
	ds_read_b128 v[152:155], v172 offset:64
	v_exp_f32_e32 v59, v59
	v_exp_f32_e32 v60, v60
	v_add_f32_e32 v246, v56, v246
	v_add_f32_e32 v247, v57, v247
	v_cvt_pk_bf16_f32 v204, v56, v57
	v_mfma_f32_32x32x16_bf16 v[16:31], v[184:187], v[238:241], v[16:31]
	ds_read_b128 v[184:187], v172 offset:4672
	v_exp_f32_e32 v61, v61
	v_exp_f32_e32 v62, v62
	v_add_f32_e32 v248, v58, v248
	v_add_f32_e32 v249, v59, v249
	v_cvt_pk_bf16_f32 v205, v58, v59
	v_mfma_f32_32x32x16_bf16 v[0:15], v[160:163], v[242:245], v[0:15]
	ds_read_b128 v[160:163], v172 offset:96
	v_exp_f32_e32 v63, v63
	v_add_f32_e32 v246, v60, v246
	v_add_f32_e32 v247, v61, v247
	v_cvt_pk_bf16_f32 v206, v60, v61
	v_add_f32_e32 v248, v62, v248
	v_mfma_f32_32x32x16_bf16 v[16:31], v[196:199], v[242:245], v[16:31]
	ds_read_b128 v[196:199], v172 offset:4704
	v_add_f32_e32 v249, v63, v249
	v_cvt_pk_bf16_f32 v207, v62, v63
	s_cmpk_eq_i32 s0, 0x10c0
	s_cbranch_scc1 .Lgq_nostore
	s_bitcmp0_b32 s0, 6
	s_cselect_b32 s6, 0x2400, 0
	v_add_u32_e32 v111, s6, v188
	v_add_u32_e32 v250, s6, v181
	v_add_u32_e32 v251, s6, v189
	v_add_u32_e32 v237, s6, v183
	s_waitcnt vmcnt(3)
	ds_write_b128 v111, v[92:95]
	s_waitcnt vmcnt(2)
	ds_write2_b64 v250, v[84:85], v[86:87] offset1:2
	s_waitcnt vmcnt(1)
	ds_write_b128 v251, v[88:91]
	s_waitcnt vmcnt(0)
	ds_write2_b64 v237, v[80:81], v[82:83] offset1:2
